# accumulator zero-init before P1/P3/P4 K-loops uses v_mov_b64 pairs (64 instead of 127 moves per unit)
# baseline (speedup 1.0000x reference)
.LBB0_175:
	s_mov_b32 s28, s29
	s_ashr_i32 s29, s29, 31
	s_lshl_b64 s[34:35], s[28:29], 20
	s_add_u32 s34, s90, s34
	s_addc_u32 s35, s91, s35
	s_and_b64 s[36:37], s[30:31], exec
	s_mov_b32 s26, s27
	s_cselect_b32 s2, s35, s43
	s_cselect_b32 s29, s34, s42
	s_ashr_i32 s27, s27, 31
	s_lshl_b64 s[36:37], s[26:27], 20
	s_add_u32 s36, s92, s36
	s_addc_u32 s37, s93, s37
	s_and_b64 s[44:45], s[30:31], exec
	s_cselect_b32 s27, s37, s41
	s_cselect_b32 s39, s36, s40
	s_add_u32 s46, s40, 0x100
	s_addc_u32 s47, s41, 0
	s_add_u32 s40, s42, 0x80080
	v_mov_b32_e32 v2, 0
	s_addc_u32 s41, s43, 0
	s_mov_b32 s52, -2
	v_mov_b32_e32 v3, v2
	v_mov_b64_e32 v[4:5], v[2:3]
	v_mov_b64_e32 v[6:7], v[2:3]
	v_mov_b64_e32 v[8:9], v[2:3]
	s_waitcnt vmcnt(0)
	v_mov_b64_e32 v[18:19], v[2:3]
	v_mov_b64_e32 v[20:21], v[2:3]
	v_mov_b64_e32 v[22:23], v[2:3]
	v_mov_b64_e32 v[24:25], v[2:3]
	v_mov_b64_e32 v[34:35], v[2:3]
	v_mov_b64_e32 v[36:37], v[2:3]
	v_mov_b64_e32 v[38:39], v[2:3]
	v_mov_b64_e32 v[40:41], v[2:3]
	v_mov_b64_e32 v[50:51], v[2:3]
	v_mov_b64_e32 v[52:53], v[2:3]
	v_mov_b64_e32 v[54:55], v[2:3]
	v_mov_b64_e32 v[56:57], v[2:3]
	v_mov_b64_e32 v[10:11], v[2:3]
	v_mov_b64_e32 v[12:13], v[2:3]
	v_mov_b64_e32 v[14:15], v[2:3]
	v_mov_b64_e32 v[16:17], v[2:3]
	v_mov_b64_e32 v[26:27], v[2:3]
	v_mov_b64_e32 v[28:29], v[2:3]
	v_mov_b64_e32 v[30:31], v[2:3]
	v_mov_b64_e32 v[32:33], v[2:3]
	v_mov_b64_e32 v[42:43], v[2:3]
	v_mov_b64_e32 v[44:45], v[2:3]
	v_mov_b64_e32 v[46:47], v[2:3]
	v_mov_b64_e32 v[48:49], v[2:3]
	v_mov_b64_e32 v[66:67], v[2:3]
	v_mov_b64_e32 v[68:69], v[2:3]
	v_mov_b64_e32 v[70:71], v[2:3]
	v_mov_b64_e32 v[72:73], v[2:3]
	v_mov_b64_e32 v[74:75], v[2:3]
	v_mov_b64_e32 v[76:77], v[2:3]
	v_mov_b64_e32 v[86:87], v[2:3]
	v_mov_b64_e32 v[88:89], v[2:3]
	v_mov_b64_e32 v[98:99], v[2:3]
	v_mov_b64_e32 v[100:101], v[2:3]
	v_mov_b64_e32 v[110:111], v[2:3]
	v_mov_b64_e32 v[112:113], v[2:3]
	v_mov_b64_e32 v[130:131], v[2:3]
	v_mov_b64_e32 v[132:133], v[2:3]
	v_mov_b64_e32 v[134:135], v[2:3]
	v_mov_b64_e32 v[136:137], v[2:3]
	v_mov_b64_e32 v[154:155], v[2:3]
	v_mov_b64_e32 v[156:157], v[2:3]
	v_mov_b64_e32 v[158:159], v[2:3]
	v_mov_b64_e32 v[160:161], v[2:3]
	v_mov_b64_e32 v[90:91], v[2:3]
	v_mov_b64_e32 v[92:93], v[2:3]
	v_mov_b64_e32 v[94:95], v[2:3]
	v_mov_b64_e32 v[96:97], v[2:3]
	v_mov_b64_e32 v[114:115], v[2:3]
	v_mov_b64_e32 v[116:117], v[2:3]
	v_mov_b64_e32 v[118:119], v[2:3]
	v_mov_b64_e32 v[120:121], v[2:3]
	v_mov_b64_e32 v[138:139], v[2:3]
	v_mov_b64_e32 v[140:141], v[2:3]
	v_mov_b64_e32 v[142:143], v[2:3]
	v_mov_b64_e32 v[144:145], v[2:3]
	v_mov_b64_e32 v[162:163], v[2:3]
	v_mov_b64_e32 v[164:165], v[2:3]
	v_mov_b64_e32 v[166:167], v[2:3]
	v_mov_b64_e32 v[168:169], v[2:3]
	v_add_u32_e32 v212, 0x18000, v218
	v_add_u32_e32 v213, 0x1c000, v218

.LBB0_650:
	s_ashr_i32 s15, s14, 31
	s_lshl_b64 s[18:19], s[14:15], 20
	s_add_u32 s18, s92, s18
	s_addc_u32 s19, s93, s19
	s_and_b64 s[20:21], s[16:17], exec
	s_cselect_b32 s15, s19, s29
	s_cselect_b32 s23, s18, s28
	s_ashr_i32 s13, s12, 31
	s_lshl_b64 s[20:21], s[12:13], 20
	s_add_u32 s20, s94, s20
	s_addc_u32 s21, s95, s21
	s_and_b64 s[30:31], s[16:17], exec
	s_cselect_b32 s13, s21, s27
	s_cselect_b32 s43, s20, s26
	s_add_u32 s44, s26, 0x100
	s_addc_u32 s45, s27, 0
	s_add_u32 s26, s28, 0x80080
	v_mov_b32_e32 v2, 0
	s_addc_u32 s27, s29, 0
	s_mov_b32 s46, -2
	s_waitcnt lgkmcnt(0)
	v_mov_b32_e32 v3, v2
	v_mov_b64_e32 v[4:5], v[2:3]
	v_mov_b64_e32 v[6:7], v[2:3]
	v_mov_b64_e32 v[8:9], v[2:3]
	v_mov_b64_e32 v[18:19], v[2:3]
	v_mov_b64_e32 v[20:21], v[2:3]
	v_mov_b64_e32 v[22:23], v[2:3]
	v_mov_b64_e32 v[24:25], v[2:3]
	v_mov_b64_e32 v[34:35], v[2:3]
	v_mov_b64_e32 v[36:37], v[2:3]
	v_mov_b64_e32 v[38:39], v[2:3]
	v_mov_b64_e32 v[40:41], v[2:3]
	v_mov_b64_e32 v[50:51], v[2:3]
	v_mov_b64_e32 v[52:53], v[2:3]
	v_mov_b64_e32 v[54:55], v[2:3]
	v_mov_b64_e32 v[56:57], v[2:3]
	v_mov_b64_e32 v[10:11], v[2:3]
	v_mov_b64_e32 v[12:13], v[2:3]
	v_mov_b64_e32 v[14:15], v[2:3]
	v_mov_b64_e32 v[16:17], v[2:3]
	v_mov_b64_e32 v[26:27], v[2:3]
	v_mov_b64_e32 v[28:29], v[2:3]
	v_mov_b64_e32 v[30:31], v[2:3]
	v_mov_b64_e32 v[32:33], v[2:3]
	v_mov_b64_e32 v[42:43], v[2:3]
	v_mov_b64_e32 v[44:45], v[2:3]
	v_mov_b64_e32 v[46:47], v[2:3]
	v_mov_b64_e32 v[48:49], v[2:3]
	v_mov_b64_e32 v[58:59], v[2:3]
	v_mov_b64_e32 v[60:61], v[2:3]
	v_mov_b64_e32 v[62:63], v[2:3]
	v_mov_b64_e32 v[64:65], v[2:3]
	v_mov_b64_e32 v[66:67], v[2:3]
	v_mov_b64_e32 v[68:69], v[2:3]
	v_mov_b64_e32 v[70:71], v[2:3]
	v_mov_b64_e32 v[72:73], v[2:3]
	v_mov_b64_e32 v[82:83], v[2:3]
	v_mov_b64_e32 v[84:85], v[2:3]
	v_mov_b64_e32 v[86:87], v[2:3]
	v_mov_b64_e32 v[88:89], v[2:3]
	v_mov_b64_e32 v[98:99], v[2:3]
	v_mov_b64_e32 v[100:101], v[2:3]
	v_mov_b64_e32 v[102:103], v[2:3]
	v_mov_b64_e32 v[104:105], v[2:3]
	v_mov_b64_e32 v[114:115], v[2:3]
	v_mov_b64_e32 v[116:117], v[2:3]
	v_mov_b64_e32 v[118:119], v[2:3]
	v_mov_b64_e32 v[120:121], v[2:3]
	v_mov_b64_e32 v[74:75], v[2:3]
	v_mov_b64_e32 v[76:77], v[2:3]
	v_mov_b64_e32 v[78:79], v[2:3]
	v_mov_b64_e32 v[80:81], v[2:3]
	v_mov_b64_e32 v[90:91], v[2:3]
	v_mov_b64_e32 v[92:93], v[2:3]
	v_mov_b64_e32 v[94:95], v[2:3]
	v_mov_b64_e32 v[96:97], v[2:3]
	v_mov_b64_e32 v[106:107], v[2:3]
	v_mov_b64_e32 v[108:109], v[2:3]
	v_mov_b64_e32 v[110:111], v[2:3]
	v_mov_b64_e32 v[112:113], v[2:3]
	v_mov_b64_e32 v[122:123], v[2:3]
	v_mov_b64_e32 v[124:125], v[2:3]
	v_mov_b64_e32 v[126:127], v[2:3]
	v_mov_b64_e32 v[128:129], v[2:3]
	v_add_u32_e32 v192, 0x18000, v195
	v_add_u32_e32 v193, 0x1c000, v195

.LBB0_807:
	s_mov_b32 s18, s19
	s_ashr_i32 s19, s19, 31
	s_lshl_b64 s[22:23], s[18:19], 20
	s_add_u32 s22, s70, s22
	s_addc_u32 s23, s71, s23
	s_and_b64 s[24:25], s[20:21], exec
	s_mov_b32 s16, s17
	s_cselect_b32 s19, s23, s35
	s_cselect_b32 s51, s22, s34
	s_ashr_i32 s17, s17, 31
	s_lshl_b64 s[24:25], s[16:17], 20
	s_add_u32 s24, s84, s24
	s_addc_u32 s25, s85, s25
	s_and_b64 s[36:37], s[20:21], exec
	s_cselect_b32 s17, s25, s31
	s_cselect_b32 s52, s24, s30
	s_add_u32 s53, s30, 0x100
	s_addc_u32 s54, s31, 0
	s_add_u32 s30, s34, 0x80080
	v_mov_b32_e32 v2, 0
	s_addc_u32 s31, s35, 0
	s_mov_b32 s55, -2
	v_mov_b32_e32 v3, v2
	v_mov_b64_e32 v[4:5], v[2:3]
	v_mov_b64_e32 v[6:7], v[2:3]
	v_mov_b64_e32 v[8:9], v[2:3]
	v_mov_b64_e32 v[18:19], v[2:3]
	v_mov_b64_e32 v[20:21], v[2:3]
	v_mov_b64_e32 v[22:23], v[2:3]
	v_mov_b64_e32 v[24:25], v[2:3]
	v_mov_b64_e32 v[34:35], v[2:3]
	v_mov_b64_e32 v[36:37], v[2:3]
	v_mov_b64_e32 v[38:39], v[2:3]
	v_mov_b64_e32 v[40:41], v[2:3]
	v_mov_b64_e32 v[50:51], v[2:3]
	v_mov_b64_e32 v[52:53], v[2:3]
	v_mov_b64_e32 v[54:55], v[2:3]
	v_mov_b64_e32 v[56:57], v[2:3]
	v_mov_b64_e32 v[10:11], v[2:3]
	v_mov_b64_e32 v[12:13], v[2:3]
	v_mov_b64_e32 v[14:15], v[2:3]
	v_mov_b64_e32 v[16:17], v[2:3]
	v_mov_b64_e32 v[26:27], v[2:3]
	v_mov_b64_e32 v[28:29], v[2:3]
	v_mov_b64_e32 v[30:31], v[2:3]
	v_mov_b64_e32 v[32:33], v[2:3]
	v_mov_b64_e32 v[42:43], v[2:3]
	v_mov_b64_e32 v[44:45], v[2:3]
	v_mov_b64_e32 v[46:47], v[2:3]
	v_mov_b64_e32 v[48:49], v[2:3]
	v_mov_b64_e32 v[58:59], v[2:3]
	v_mov_b64_e32 v[60:61], v[2:3]
	v_mov_b64_e32 v[62:63], v[2:3]
	v_mov_b64_e32 v[64:65], v[2:3]
	v_mov_b64_e32 v[66:67], v[2:3]
	v_mov_b64_e32 v[68:69], v[2:3]
	v_mov_b64_e32 v[70:71], v[2:3]
	v_mov_b64_e32 v[72:73], v[2:3]
	v_mov_b64_e32 v[82:83], v[2:3]
	v_mov_b64_e32 v[84:85], v[2:3]
	v_mov_b64_e32 v[86:87], v[2:3]
	v_mov_b64_e32 v[88:89], v[2:3]
	v_mov_b64_e32 v[98:99], v[2:3]
	v_mov_b64_e32 v[100:101], v[2:3]
	v_mov_b64_e32 v[102:103], v[2:3]
	v_mov_b64_e32 v[104:105], v[2:3]
	v_mov_b64_e32 v[114:115], v[2:3]
	v_mov_b64_e32 v[116:117], v[2:3]
	v_mov_b64_e32 v[118:119], v[2:3]
	v_mov_b64_e32 v[120:121], v[2:3]
	v_mov_b64_e32 v[74:75], v[2:3]
	v_mov_b64_e32 v[76:77], v[2:3]
	v_mov_b64_e32 v[78:79], v[2:3]
	v_mov_b64_e32 v[80:81], v[2:3]
	v_mov_b64_e32 v[90:91], v[2:3]
	v_mov_b64_e32 v[92:93], v[2:3]
	v_mov_b64_e32 v[94:95], v[2:3]
	v_mov_b64_e32 v[96:97], v[2:3]
	v_mov_b64_e32 v[106:107], v[2:3]
	v_mov_b64_e32 v[108:109], v[2:3]
	v_mov_b64_e32 v[110:111], v[2:3]
	v_mov_b64_e32 v[112:113], v[2:3]
	v_mov_b64_e32 v[122:123], v[2:3]
	v_mov_b64_e32 v[124:125], v[2:3]
	v_mov_b64_e32 v[126:127], v[2:3]
	v_mov_b64_e32 v[128:129], v[2:3]
	v_add_u32_e32 v148, 0x18000, v150
	v_add_u32_e32 v149, 0x1c000, v150
